# speedup vs baseline: 1.0036x; 1.0036x over previous
; #define LAS __attribute__((address_space(3)))
; #define GAS __attribute__((address_space(1)))
; __device__ __forceinline__ void attn_unit(LAS unsigned char* lds, bf16_t* Qm, const bf16_t* __restrict__ Kb, const bf16_t* __restrict__ Vt,
;                                           int b, int h, int qb, int lgS, float lam, float oscale, const float* __restrict__ subg, float* stash) {
;     ...
;         {
; #pragma unroll
;             for (int blk = 0; blk < 4; ++blk) o[blk] = __builtin_amdgcn_mfma_f32_32x32x16_bf16(vfa[blk], __builtin_bit_cast(bf16x8, pk[0]), o[blk], 0, 0, 0);
; #pragma unroll
;             for (int ks = 1; ks < 4; ++ks)
; #pragma unroll
;                 for (int blk = 0; blk < 4; ++blk) {
;                     const bf16x8 vf = *(const LAS bf16x8*)(lds + vs0 + vr + blk * 32 * VP + ks * 32);
;                     o[blk] = __builtin_amdgcn_mfma_f32_32x32x16_bf16(vf, __builtin_bit_cast(bf16x8, pk[ks]), o[blk], 0, 0, 0);
;                 }
;         }
;         __syncthreads();
;         lrun += __shfl_xor(lrun, 32);
;         inv = 1.0f / lrun;
;         if (c == 0) {
;             int tq_ = threadIdx.x; asm volatile("" : "+v"(tq_)); float* st_ = stash + tq_ * 64;
; #pragma unroll
;             for (int i = 0; i < 4; ++i)
; #pragma unroll
;                 for (int r = 0; r < 16; r += 4) *(GAS f32x4*)(st_ + i * 16 + r) = (f32x4){o[i][r] * inv, o[i][r + 1] * inv, o[i][r + 2] * inv, o[i][r + 3] * inv};
.Lmy_skip_pf:
	v_add_u32_e32 v72, s25, v220
	ds_read_b128 v[80:83], v72 offset:25376
	ds_read_b128 v[84:87], v72 offset:29984
	ds_read_b128 v[88:91], v72 offset:34592
	ds_read_b128 v[92:95], v72 offset:39200
	ds_read_b128 v[96:99], v72 offset:25408
	ds_read_b128 v[100:103], v72 offset:30016
	ds_read_b128 v[104:107], v72 offset:34624
	ds_read_b128 v[108:111], v72 offset:39232
	ds_read_b128 v[204:207], v72 offset:25440
	ds_read_b128 v[208:211], v72 offset:30048
	ds_read_b128 v[212:215], v72 offset:34656
	ds_read_b128 v[216:219], v72 offset:39264
	v_mfma_f32_32x32x16_bf16 v[0:15], v[196:199], v[200:203], v[0:15]
	v_mfma_f32_32x32x16_bf16 v[48:63], v[192:195], v[200:203], v[48:63]
	v_mfma_f32_32x32x16_bf16 v[32:47], v[188:191], v[200:203], v[32:47]
	v_mfma_f32_32x32x16_bf16 v[16:31], v[184:187], v[200:203], v[16:31]
	s_waitcnt lgkmcnt(8)
	v_mfma_f32_32x32x16_bf16 v[0:15], v[80:83], v[180:183], v[0:15]
	v_mfma_f32_32x32x16_bf16 v[48:63], v[84:87], v[180:183], v[48:63]
	v_mfma_f32_32x32x16_bf16 v[32:47], v[88:91], v[180:183], v[32:47]
	v_mfma_f32_32x32x16_bf16 v[16:31], v[92:95], v[180:183], v[16:31]
	s_waitcnt lgkmcnt(4)
	v_mfma_f32_32x32x16_bf16 v[0:15], v[96:99], v[172:175], v[0:15]
	v_mfma_f32_32x32x16_bf16 v[48:63], v[100:103], v[172:175], v[48:63]
	v_mfma_f32_32x32x16_bf16 v[32:47], v[104:107], v[172:175], v[32:47]
	v_mfma_f32_32x32x16_bf16 v[16:31], v[108:111], v[172:175], v[16:31]
	s_waitcnt lgkmcnt(0)
	s_barrier
	v_mfma_f32_32x32x16_bf16 v[0:15], v[204:207], v[164:167], v[0:15]
	v_mfma_f32_32x32x16_bf16 v[48:63], v[208:211], v[164:167], v[48:63]
	v_mfma_f32_32x32x16_bf16 v[32:47], v[212:215], v[164:167], v[32:47]
	v_mfma_f32_32x32x16_bf16 v[16:31], v[216:219], v[164:167], v[16:31]
	ds_bpermute_b32 v64, v246, v249
	s_waitcnt lgkmcnt(0)
	v_add_f32_e32 v64, v249, v64
	v_div_scale_f32 v65, s[28:29], v64, v64, 1.0
	v_rcp_f32_e32 v66, v65
	s_mov_b64 s[28:29], -1
	v_fma_f32 v67, -v65, v66, 1.0
	v_fmac_f32_e32 v66, v67, v66
	v_div_scale_f32 v67, vcc, 1.0, v64, 1.0
	v_mul_f32_e32 v68, v67, v66
	v_fma_f32 v69, -v65, v68, v67
	v_fmac_f32_e32 v68, v69, v66
	v_fma_f32 v65, -v65, v68, v67
	v_div_fmas_f32 v65, v65, v66, v68
	v_div_fixup_f32 v64, v65, v64, 1.0
	s_and_b64 vcc, exec, s[26:27]
	s_cbranch_vccz .LBB0_333
	v_mov_b32_e32 v65, v254
	s_mov_b64 s[28:29], 0
	v_lshlrev_b32_e32 v70, 4, v65
	v_pk_mul_f32 v[66:67], v[0:1], v[64:65] op_sel_hi:[1,0]
	v_pk_mul_f32 v[68:69], v[2:3], v[64:65] op_sel_hi:[1,0]
	global_store_dwordx4 v70, v[66:69], s[66:67]
	s_nop 1
	v_pk_mul_f32 v[66:67], v[4:5], v[64:65] op_sel_hi:[1,0]
	v_pk_mul_f32 v[68:69], v[6:7], v[64:65] op_sel_hi:[1,0]
	s_add_u32 s100, s66, 0x2000
	s_addc_u32 s101, s67, 0
	global_store_dwordx4 v70, v[66:69], s[100:101]
	s_nop 1
	v_pk_mul_f32 v[66:67], v[8:9], v[64:65] op_sel_hi:[1,0]
	v_pk_mul_f32 v[68:69], v[10:11], v[64:65] op_sel_hi:[1,0]
	s_add_u32 s100, s66, 0x4000
	s_addc_u32 s101, s67, 0
	global_store_dwordx4 v70, v[66:69], s[100:101]
	s_nop 1
	v_pk_mul_f32 v[66:67], v[12:13], v[64:65] op_sel_hi:[1,0]
	v_pk_mul_f32 v[68:69], v[14:15], v[64:65] op_sel_hi:[1,0]
	s_add_u32 s100, s66, 0x6000
	s_addc_u32 s101, s67, 0
	global_store_dwordx4 v70, v[66:69], s[100:101]
	s_nop 1
	v_pk_mul_f32 v[66:67], v[48:49], v[64:65] op_sel_hi:[1,0]
	v_pk_mul_f32 v[68:69], v[50:51], v[64:65] op_sel_hi:[1,0]
	s_add_u32 s100, s66, 0x8000
	s_addc_u32 s101, s67, 0
	global_store_dwordx4 v70, v[66:69], s[100:101]
	s_nop 1
	v_pk_mul_f32 v[66:67], v[52:53], v[64:65] op_sel_hi:[1,0]
	v_pk_mul_f32 v[68:69], v[54:55], v[64:65] op_sel_hi:[1,0]
	s_add_u32 s100, s66, 0xa000
	s_addc_u32 s101, s67, 0
	global_store_dwordx4 v70, v[66:69], s[100:101]
	s_nop 1
	v_pk_mul_f32 v[66:67], v[56:57], v[64:65] op_sel_hi:[1,0]
	v_pk_mul_f32 v[68:69], v[58:59], v[64:65] op_sel_hi:[1,0]
	s_add_u32 s100, s66, 0xc000
	s_addc_u32 s101, s67, 0
	global_store_dwordx4 v70, v[66:69], s[100:101]
	s_nop 1
	v_pk_mul_f32 v[66:67], v[60:61], v[64:65] op_sel_hi:[1,0]
	v_pk_mul_f32 v[68:69], v[62:63], v[64:65] op_sel_hi:[1,0]
	s_add_u32 s100, s66, 0xe000
	s_addc_u32 s101, s67, 0
	global_store_dwordx4 v70, v[66:69], s[100:101]
	s_nop 1
	v_pk_mul_f32 v[66:67], v[32:33], v[64:65] op_sel_hi:[1,0]
	v_pk_mul_f32 v[68:69], v[34:35], v[64:65] op_sel_hi:[1,0]
	s_add_u32 s100, s66, 0x10000
	s_addc_u32 s101, s67, 0
	global_store_dwordx4 v70, v[66:69], s[100:101]
	s_nop 1
	v_pk_mul_f32 v[66:67], v[36:37], v[64:65] op_sel_hi:[1,0]
	v_pk_mul_f32 v[68:69], v[38:39], v[64:65] op_sel_hi:[1,0]
	s_add_u32 s100, s66, 0x12000
	s_addc_u32 s101, s67, 0
	global_store_dwordx4 v70, v[66:69], s[100:101]
	s_nop 1
	v_pk_mul_f32 v[66:67], v[40:41], v[64:65] op_sel_hi:[1,0]
	v_pk_mul_f32 v[68:69], v[42:43], v[64:65] op_sel_hi:[1,0]
	s_add_u32 s100, s66, 0x14000
	s_addc_u32 s101, s67, 0
	global_store_dwordx4 v70, v[66:69], s[100:101]
	s_nop 1
	v_pk_mul_f32 v[66:67], v[44:45], v[64:65] op_sel_hi:[1,0]
	v_pk_mul_f32 v[68:69], v[46:47], v[64:65] op_sel_hi:[1,0]
	s_add_u32 s100, s66, 0x16000
	s_addc_u32 s101, s67, 0
	global_store_dwordx4 v70, v[66:69], s[100:101]
	s_nop 1
	v_pk_mul_f32 v[66:67], v[16:17], v[64:65] op_sel_hi:[1,0]
	v_pk_mul_f32 v[68:69], v[18:19], v[64:65] op_sel_hi:[1,0]
	s_add_u32 s100, s66, 0x18000
	s_addc_u32 s101, s67, 0
	global_store_dwordx4 v70, v[66:69], s[100:101]
	s_nop 1
	v_pk_mul_f32 v[66:67], v[20:21], v[64:65] op_sel_hi:[1,0]
	v_pk_mul_f32 v[68:69], v[22:23], v[64:65] op_sel_hi:[1,0]
	s_add_u32 s100, s66, 0x1a000
	s_addc_u32 s101, s67, 0
	global_store_dwordx4 v70, v[66:69], s[100:101]
	s_nop 1
	v_pk_mul_f32 v[66:67], v[24:25], v[64:65] op_sel_hi:[1,0]
	v_pk_mul_f32 v[68:69], v[26:27], v[64:65] op_sel_hi:[1,0]
	s_add_u32 s100, s66, 0x1c000
	s_addc_u32 s101, s67, 0
	global_store_dwordx4 v70, v[66:69], s[100:101]
	s_nop 1
	v_pk_mul_f32 v[66:67], v[28:29], v[64:65] op_sel_hi:[1,0]
	v_pk_mul_f32 v[68:69], v[30:31], v[64:65] op_sel_hi:[1,0]
	s_add_u32 s100, s66, 0x1e000
	s_addc_u32 s101, s67, 0
	global_store_dwordx4 v70, v[66:69], s[100:101]
	s_branch .LBB0_333
